# wi 11/21 + first grid barrier: reuse the 16 XCD counters read by the poll loop instead of re-reading them
# speedup vs baseline: 1.0004x; 1.0004x over previous
.LBB0_197:
	v_mov_b32_e32 v19, 0
	v_mov_b32_e32 v20, v17
	v_mov_b32_e32 v21, v2
	v_mov_b32_e32 v22, v3
	v_mov_b32_e32 v23, v4
	v_mov_b32_e32 v24, v5
	v_mov_b32_e32 v25, v6
	v_mov_b32_e32 v26, v7
	v_mov_b32_e32 v27, v8
	v_mov_b32_e32 v28, v9
	v_mov_b32_e32 v29, v10
	v_mov_b32_e32 v30, v11
	v_mov_b32_e32 v31, v12
	v_mov_b32_e32 v32, v13
	v_mov_b32_e32 v33, v14
	v_mov_b32_e32 v34, v15
	v_mov_b32_e32 v35, v16
	s_cmp_eq_u32 s33, 0
	s_cselect_b64 vcc, -1, 0
	s_cmp_eq_u32 s33, 1
	v_cndmask_b32_e32 v18, 0, v17, vcc
	s_cselect_b64 vcc, -1, 0
	s_cmp_eq_u32 s33, 2
	v_cndmask_b32_e32 v18, v18, v2, vcc
	s_cselect_b64 vcc, -1, 0
	s_cmp_eq_u32 s33, 3
	v_cndmask_b32_e32 v18, v18, v3, vcc
	s_cselect_b64 vcc, -1, 0
	s_cmp_eq_u32 s33, 4
	v_cndmask_b32_e32 v18, v18, v4, vcc
	s_cselect_b64 vcc, -1, 0
	s_cmp_eq_u32 s33, 5
	v_cndmask_b32_e32 v18, v18, v5, vcc
	s_cselect_b64 vcc, -1, 0
	s_cmp_eq_u32 s33, 6
	v_cndmask_b32_e32 v18, v18, v6, vcc
	s_cselect_b64 vcc, -1, 0
	s_cmp_eq_u32 s33, 7
	v_cndmask_b32_e32 v18, v18, v7, vcc
	s_cselect_b64 vcc, -1, 0
	s_cmp_eq_u32 s33, 8
	v_cndmask_b32_e32 v18, v18, v8, vcc
	s_cselect_b64 vcc, -1, 0
	s_cmp_eq_u32 s33, 9
	v_cndmask_b32_e32 v18, v18, v9, vcc
	s_cselect_b64 vcc, -1, 0
	s_cmp_eq_u32 s33, 10
	v_cndmask_b32_e32 v18, v18, v10, vcc
	s_cselect_b64 vcc, -1, 0
	s_cmp_eq_u32 s33, 11
	v_cndmask_b32_e32 v18, v18, v11, vcc
	s_cselect_b64 vcc, -1, 0
	s_cmp_eq_u32 s33, 12
	v_cndmask_b32_e32 v18, v18, v12, vcc
	s_cselect_b64 vcc, -1, 0
	s_cmp_eq_u32 s33, 13
	v_cndmask_b32_e32 v18, v18, v13, vcc
	s_cselect_b64 vcc, -1, 0
	s_cmp_eq_u32 s33, 14
	v_cndmask_b32_e32 v18, v18, v14, vcc
	s_cselect_b64 vcc, -1, 0
	s_cmp_eq_u32 s33, 15
	v_cndmask_b32_e32 v18, v18, v15, vcc
	s_cselect_b64 vcc, -1, 0
	v_cndmask_b32_e32 v18, v18, v16, vcc
	v_cmp_ne_u32_e32 vcc, 0, v17
	s_and_b32 s4, s39, 7
	s_cmp_eq_u32 s4, 0
	v_cndmask_b32_e64 v17, 0, 1, vcc
	v_cmp_ne_u32_e32 vcc, 0, v2
	s_cselect_b64 s[4:5], -1, 0
	s_lshr_b32 s14, s39, 3
	v_addc_co_u32_e32 v2, vcc, 0, v17, vcc
	v_cmp_ne_u32_e32 vcc, 0, v3
	s_waitcnt vmcnt(12)
	v_cmp_eq_u32_e64 s[6:7], s14, v23
	v_cndmask_b32_e64 v3, 0, 1, vcc
	v_cmp_ne_u32_e32 vcc, 0, v4
	s_waitcnt vmcnt(11)
	v_cmp_eq_u32_e64 s[8:9], s14, v24
	s_waitcnt vmcnt(10)
	v_cmp_eq_u32_e64 s[10:11], s14, v25
	v_addc_co_u32_e32 v2, vcc, v2, v3, vcc
	v_cmp_ne_u32_e32 vcc, 0, v5
	s_waitcnt vmcnt(9)
	v_cmp_eq_u32_e64 s[12:13], s14, v26
	s_waitcnt vmcnt(0)
	v_or_b32_e32 v4, v35, v34
	v_cndmask_b32_e64 v3, 0, 1, vcc
	v_cmp_ne_u32_e32 vcc, 0, v6
	v_or_b32_e32 v4, v4, v33
	v_or_b32_e32 v4, v4, v32
	v_addc_co_u32_e32 v2, vcc, v2, v3, vcc
	v_cmp_ne_u32_e32 vcc, 0, v7
	v_or_b32_e32 v4, v4, v31
	v_or_b32_e32 v4, v4, v30
	v_cndmask_b32_e64 v3, 0, 1, vcc
	v_cmp_ne_u32_e32 vcc, 0, v8
	v_or_b32_e32 v4, v4, v29
	v_or_b32_e32 v4, v4, v28
	v_addc_co_u32_e32 v2, vcc, v2, v3, vcc
	v_cmp_ne_u32_e32 vcc, 0, v9
	v_cmp_eq_u32_e64 s[16:17], 0, v4
	s_nop 0
	v_cndmask_b32_e64 v3, 0, 1, vcc
	v_cmp_ne_u32_e32 vcc, 0, v10
	s_nop 1
	v_addc_co_u32_e32 v2, vcc, v2, v3, vcc
	v_cmp_ne_u32_e32 vcc, 0, v11
	s_nop 1
	v_cndmask_b32_e64 v3, 0, 1, vcc
	v_cmp_ne_u32_e32 vcc, 0, v12
	s_nop 1
	v_addc_co_u32_e32 v2, vcc, v2, v3, vcc
	v_cmp_ne_u32_e32 vcc, 0, v13
	s_nop 1
	v_cndmask_b32_e64 v3, 0, 1, vcc
	v_cmp_ne_u32_e32 vcc, 0, v14
	s_nop 1
	v_addc_co_u32_e32 v2, vcc, v2, v3, vcc
	v_cmp_ne_u32_e32 vcc, 0, v15
	s_nop 1
	v_cndmask_b32_e64 v3, 0, 1, vcc
	v_cmp_ne_u32_e32 vcc, 0, v16
	s_nop 1
	v_addc_co_u32_e32 v2, vcc, v2, v3, vcc
	v_cmp_eq_u32_e32 vcc, s14, v20
	s_and_b64 s[20:21], s[4:5], vcc
	v_cmp_eq_u32_e32 vcc, s14, v21
	v_cmp_eq_u32_e64 s[4:5], s14, v22
	v_cmp_eq_u32_e64 s[14:15], s14, v27
	s_and_b64 s[14:15], s[16:17], s[14:15]
	s_and_b64 s[12:13], s[14:15], s[12:13]
	s_and_b64 s[10:11], s[12:13], s[10:11]
	s_and_b64 s[8:9], s[10:11], s[8:9]
	s_and_b64 s[6:7], s[8:9], s[6:7]
	s_and_b64 s[4:5], s[6:7], s[4:5]
	s_and_b64 s[4:5], s[4:5], vcc
	s_and_b64 s[4:5], s[4:5], s[20:21]
	v_cndmask_b32_e64 v4, 0, 1, s[4:5]
	s_add_i32 s4, 0, 0x23020
	v_max_u32_e32 v3, 1, v18
	v_mov_b32_e32 v5, s4
	s_add_i32 s4, 0, 0x23024
	v_max_u32_e32 v2, 1, v2
	ds_write_b32 v5, v3
	v_mov_b32_e32 v5, s4
	s_add_i32 s4, 0, 0x2302c
	ds_write_b32 v5, v2
	v_mov_b32_e32 v5, s4
	ds_write_b32 v5, v4

.LBB0_532:
	v_mov_b32_e32 v18, 0
	v_mov_b32_e32 v19, v16
	v_mov_b32_e32 v20, v1
	v_mov_b32_e32 v21, v2
	v_mov_b32_e32 v22, v3
	v_mov_b32_e32 v23, v4
	v_mov_b32_e32 v24, v5
	v_mov_b32_e32 v25, v6
	v_mov_b32_e32 v26, v7
	v_mov_b32_e32 v27, v8
	v_mov_b32_e32 v28, v9
	v_mov_b32_e32 v29, v10
	v_mov_b32_e32 v30, v11
	v_mov_b32_e32 v31, v12
	v_mov_b32_e32 v32, v13
	v_mov_b32_e32 v33, v14
	v_mov_b32_e32 v34, v15
	s_cmp_eq_u32 s33, 0
	s_cselect_b64 vcc, -1, 0
	s_cmp_eq_u32 s33, 1
	v_cndmask_b32_e32 v17, 0, v16, vcc
	s_cselect_b64 vcc, -1, 0
	s_cmp_eq_u32 s33, 2
	v_cndmask_b32_e32 v17, v17, v1, vcc
	s_cselect_b64 vcc, -1, 0
	s_cmp_eq_u32 s33, 3
	v_cndmask_b32_e32 v17, v17, v2, vcc
	s_cselect_b64 vcc, -1, 0
	s_cmp_eq_u32 s33, 4
	v_cndmask_b32_e32 v17, v17, v3, vcc
	s_cselect_b64 vcc, -1, 0
	s_cmp_eq_u32 s33, 5
	v_cndmask_b32_e32 v17, v17, v4, vcc
	s_cselect_b64 vcc, -1, 0
	s_cmp_eq_u32 s33, 6
	v_cndmask_b32_e32 v17, v17, v5, vcc
	s_cselect_b64 vcc, -1, 0
	s_cmp_eq_u32 s33, 7
	v_cndmask_b32_e32 v17, v17, v6, vcc
	s_cselect_b64 vcc, -1, 0
	s_cmp_eq_u32 s33, 8
	v_cndmask_b32_e32 v17, v17, v7, vcc
	s_cselect_b64 vcc, -1, 0
	s_cmp_eq_u32 s33, 9
	v_cndmask_b32_e32 v17, v17, v8, vcc
	s_cselect_b64 vcc, -1, 0
	s_cmp_eq_u32 s33, 10
	v_cndmask_b32_e32 v17, v17, v9, vcc
	s_cselect_b64 vcc, -1, 0
	s_cmp_eq_u32 s33, 11
	v_cndmask_b32_e32 v17, v17, v10, vcc
	s_cselect_b64 vcc, -1, 0
	s_cmp_eq_u32 s33, 12
	v_cndmask_b32_e32 v17, v17, v11, vcc
	s_cselect_b64 vcc, -1, 0
	s_cmp_eq_u32 s33, 13
	v_cndmask_b32_e32 v17, v17, v12, vcc
	s_cselect_b64 vcc, -1, 0
	s_cmp_eq_u32 s33, 14
	v_cndmask_b32_e32 v17, v17, v13, vcc
	s_cselect_b64 vcc, -1, 0
	s_cmp_eq_u32 s33, 15
	v_cndmask_b32_e32 v17, v17, v14, vcc
	s_cselect_b64 vcc, -1, 0
	v_cndmask_b32_e32 v17, v17, v15, vcc
	v_cmp_ne_u32_e32 vcc, 0, v16
	s_and_b32 s2, s39, 7
	s_cmp_eq_u32 s2, 0
	v_cndmask_b32_e64 v16, 0, 1, vcc
	v_cmp_ne_u32_e32 vcc, 0, v1
	s_cselect_b64 s[2:3], -1, 0
	s_lshr_b32 s12, s39, 3
	v_addc_co_u32_e32 v1, vcc, 0, v16, vcc
	v_cmp_ne_u32_e32 vcc, 0, v2
	s_waitcnt vmcnt(12)
	v_cmp_eq_u32_e64 s[4:5], s12, v22
	v_cndmask_b32_e64 v2, 0, 1, vcc
	v_cmp_ne_u32_e32 vcc, 0, v3
	s_waitcnt vmcnt(11)
	v_cmp_eq_u32_e64 s[6:7], s12, v23
	s_waitcnt vmcnt(10)
	v_cmp_eq_u32_e64 s[8:9], s12, v24
	v_addc_co_u32_e32 v1, vcc, v1, v2, vcc
	v_cmp_ne_u32_e32 vcc, 0, v4
	s_waitcnt vmcnt(9)
	v_cmp_eq_u32_e64 s[10:11], s12, v25
	s_waitcnt vmcnt(0)
	v_or_b32_e32 v3, v34, v33
	v_cndmask_b32_e64 v2, 0, 1, vcc
	v_cmp_ne_u32_e32 vcc, 0, v5
	v_or_b32_e32 v3, v3, v32
	v_or_b32_e32 v3, v3, v31
	v_addc_co_u32_e32 v1, vcc, v1, v2, vcc
	v_cmp_ne_u32_e32 vcc, 0, v6
	v_or_b32_e32 v3, v3, v30
	v_or_b32_e32 v3, v3, v29
	v_cndmask_b32_e64 v2, 0, 1, vcc
	v_cmp_ne_u32_e32 vcc, 0, v7
	v_or_b32_e32 v3, v3, v28
	v_or_b32_e32 v3, v3, v27
	v_addc_co_u32_e32 v1, vcc, v1, v2, vcc
	v_cmp_ne_u32_e32 vcc, 0, v8
	v_cmp_eq_u32_e64 s[14:15], 0, v3
	s_nop 0
	v_cndmask_b32_e64 v2, 0, 1, vcc
	v_cmp_ne_u32_e32 vcc, 0, v9
	s_nop 1
	v_addc_co_u32_e32 v1, vcc, v1, v2, vcc
	v_cmp_ne_u32_e32 vcc, 0, v10
	s_nop 1
	v_cndmask_b32_e64 v2, 0, 1, vcc
	v_cmp_ne_u32_e32 vcc, 0, v11
	s_nop 1
	v_addc_co_u32_e32 v1, vcc, v1, v2, vcc
	v_cmp_ne_u32_e32 vcc, 0, v12
	s_nop 1
	v_cndmask_b32_e64 v2, 0, 1, vcc
	v_cmp_ne_u32_e32 vcc, 0, v13
	s_nop 1
	v_addc_co_u32_e32 v1, vcc, v1, v2, vcc
	v_cmp_ne_u32_e32 vcc, 0, v14
	s_nop 1
	v_cndmask_b32_e64 v2, 0, 1, vcc
	v_cmp_ne_u32_e32 vcc, 0, v15
	s_nop 1
	v_addc_co_u32_e32 v1, vcc, v1, v2, vcc
	v_cmp_eq_u32_e32 vcc, s12, v19
	s_and_b64 s[18:19], s[2:3], vcc
	v_cmp_eq_u32_e32 vcc, s12, v20
	v_cmp_eq_u32_e64 s[2:3], s12, v21
	v_cmp_eq_u32_e64 s[12:13], s12, v26
	s_and_b64 s[12:13], s[14:15], s[12:13]
	s_and_b64 s[10:11], s[12:13], s[10:11]
	s_and_b64 s[8:9], s[10:11], s[8:9]
	s_and_b64 s[6:7], s[8:9], s[6:7]
	s_and_b64 s[4:5], s[6:7], s[4:5]
	s_and_b64 s[2:3], s[4:5], s[2:3]
	s_and_b64 s[2:3], s[2:3], vcc
	s_and_b64 s[2:3], s[2:3], s[18:19]
	v_cndmask_b32_e64 v3, 0, 1, s[2:3]
	s_add_i32 s2, 0, 0x23020
	v_max_u32_e32 v2, 1, v17
	v_mov_b32_e32 v4, s2
	s_add_i32 s2, 0, 0x23024
	v_max_u32_e32 v1, 1, v1
	ds_write_b32 v4, v2
	v_mov_b32_e32 v4, s2
	s_add_i32 s2, 0, 0x2302c
	ds_write_b32 v4, v1
	v_mov_b32_e32 v4, s2
	ds_write_b32 v4, v3
